# v98 + layer-0 pool-elem context items moved to workgroups 32-63 and processed first (workgroups 0-7 keep only 4 items before their two pool GEMM units)
# baseline (speedup 1.0000x reference)
; __global__ void __launch_bounds__(NWAVES * 64, 2) fwd_kernel(Args args) {
;     ...
;                 const int nitems = (nrows / 64) * 4;
;                 f32x4 pv[10]; float rreg;
;     ...
;                 { const int it0_ = bx < nitems ? bx : 0; PL_PREFETCH(it0_); }
;                 for (int it = bx; it < nitems; it += G) {
.LBB0_1174:
	s_andn2_b64 vcc, exec, s[0:1]
	s_movk_i32 s30, 0x1fff
	s_movk_i32 s44, 0xff00
	s_cbranch_vccnz .LBB0_1372
	v_readlane_b32 s0, v255, 8
	v_readlane_b32 s1, v255, 9
	s_mov_b32 s2, s0
	s_cmp_lg_u32 s0, 0
	s_cselect_b64 s[0:1], -1, 0
	s_cmp_eq_u32 s2, 0
	s_movk_i32 s2, 0x420
	s_cselect_b32 s4, s2, 0x400
	s_waitcnt vmcnt(0)
	v_mov_b32_e32 v42, v215
	s_mov_b32 s23, s84
	s_mov_b32 s5, s82
	s_and_b32 s100, s84, 7
	s_lshl_b32 s100, s100, 3
	s_bfe_u32 s101, s84, 0x30003
	s_add_i32 s100, s100, s101
	s_lshl_b32 s100, s100, 4
	s_lshr_b32 s101, s84, 6
	s_add_i32 s23, s100, s101
	s_mov_b32 s5, 4
	s_bfe_u32 s101, s84, 0x10002
	s_lshl_b32 s101, s101, 4
	s_and_b32 s8, s84, 3
	s_add_i32 s101, s101, s8
	s_bfe_u32 s8, s84, 0x20003
	s_lshl_b32 s8, s8, 2
	s_add_i32 s101, s101, s8
	s_addk_i32 s101, 0x400
	s_add_i32 s8, s23, 16
	s_cmpk_eq_u32 s4, 0x400
	s_cselect_b32 s4, s8, s4
	s_cselect_b32 s8, 64, 0
	s_sub_i32 s100, s84, 32
	s_add_i32 s100, s100, s8
	s_cmp_lt_u32 s100, 32
	s_cselect_b32 s8, s101, s23
	s_movk_i32 s100, 0x7fff
	s_cselect_b32 s101, s23, s100
	s_cselect_b32 s100, 0x100, 0
	s_mov_b32 s23, s8

; #define PL_DECODE(it_, g_, t0_, ss_, Ls_, b_) const int g_ = (it_) & 3, t0_ = ((it_) >> 2) * 64; int ss_, Ls_, b_; \
;         if (t0_ < MLAT) { ss_ = t0_ & ~(SEQ - 1); Ls_ = SEQ; b_ = t0_ >> 13; } else { ss_ = MLAT + ((t0_ - MLAT) & ~(CTXL - 1)); Ls_ = CTXL; b_ = 2; }
; __global__ void __launch_bounds__(NWAVES * 64, 2) fwd_kernel(Args args) {
;     ...
;                 { const int it0_ = bx < nitems ? bx : 0; PL_PREFETCH(it0_); }
;                 for (int it = bx; it < nitems; it += G) {
;                     PL_DECODE(it, g, t0, seq_start, Ls, b) const int hw = 1 << g, T0 = t0 - seq_start;
;                     if (tid < 80) rs[tid] = rreg;
; #pragma unroll
;                     for (int k = 0; k < 10; ++k) tile[tid + 512 * k] = pv[k];
;                     __syncthreads();
;                     { const int itn_ = it + G < nitems ? it + G : it; PL_PREFETCH(itn_); }
.LBB0_1228:
	s_or_b64 exec, exec, s[6:7]
	s_add_i32 s21, s23, s5
	s_add_i32 s100, s100, 1
	s_cmp_eq_u32 s100, 0x101
	s_cselect_b32 s21, s101, s21
	s_cmp_eq_u32 s100, 4
	s_cselect_b32 s21, s101, s21
	s_cmp_gt_u32 s100, 0x104
	s_cselect_b32 s21, 0x7fff, s21
	s_lshl_b32 s20, s21, 4
	s_sub_i32 s20, s20, s19
	s_cmp_ge_i32 s21, s4
	s_cselect_b64 s[6:7], -1, 0
	s_cmp_lt_i32 s21, s4
	s_cselect_b32 s8, s21, s23
	s_lshl_b32 s14, s8, 4
	s_and_b32 s31, s14, 0xffffffc0
	s_cmpk_lt_i32 s31, 0x4000
	s_cselect_b32 s15, 0xffffe000, s44
	s_cselect_b32 s33, s30, 0xff
	s_and_b32 s36, s15, s14
	s_sub_i32 s34, s31, s36
	s_add_i32 s37, s34, -8
	v_add_u32_e32 v129, s37, v65
	ds_write_b128 v66, v[36:39] offset:512
	ds_write_b128 v66, v[32:35] offset:8704
	ds_write_b128 v66, v[28:31] offset:16896
	ds_write_b128 v66, v[24:27] offset:25088
	ds_write_b128 v66, v[20:23] offset:33280
	ds_write_b128 v66, v[16:19] offset:41472
	ds_write_b128 v66, v[12:15] offset:49664
	ds_write_b128 v66, v[8:11] offset:57856
	ds_write_b128 v88, v[4:7]
	ds_write_b128 v89, v[0:3]
	v_min_i32_e32 v0, s33, v129
	v_cmp_lt_i32_e32 vcc, -1, v129
	s_lshl_b32 s8, s8, 8
	s_and_b32 s35, s8, 0x300
	v_cndmask_b32_e32 v130, 0, v0, vcc
	v_add_u32_e32 v0, s36, v130
	s_mov_b64 s[14:15], -1
	s_and_b64 vcc, exec, s[0:1]
	v_ashrrev_i32_e32 v1, 31, v0
	s_waitcnt lgkmcnt(0)
	s_barrier
	s_cbranch_vccz .LBB0_1230
	s_load_dwordx2 s[14:15], s[2:3], 0xb8
	v_lshlrev_b64 v[2:3], 11, v[0:1]
	s_lshl_b32 s8, s35, 1
	v_mov_b32_e32 v61, v213
	s_waitcnt lgkmcnt(0)
	v_lshl_add_u64 v[2:3], s[14:15], 0, v[2:3]
	v_lshl_add_u64 v[2:3], v[2:3], 0, s[8:9]
	v_lshl_add_u64 v[2:3], v[2:3], 0, v[60:61]
	v_add_co_u32_e32 v2, vcc, 0x14200000, v2
	s_mov_b64 s[14:15], 0
	s_nop 0
	v_addc_co_u32_e32 v3, vcc, 0, v3, vcc
	global_load_dwordx2 v[2:3], v[2:3], off
	s_waitcnt vmcnt(0)
	v_lshlrev_b32_e32 v36, 16, v2
	v_and_b32_e32 v37, 0xffff0000, v2
	v_lshlrev_b32_e32 v38, 16, v3
	v_and_b32_e32 v39, 0xffff0000, v3

; #define PHASE_END   } if (ph + 1 < hi) { if (lo < 0) grid.sync(); int tb_ = tid0; asm volatile("" : "+v"(tb_)); xcd_barrier(xbar, tb_); if ((PROBE_MASK >> 8) & 1) xcd_barrier(xbar, tb_); } } ++ph;
; __global__ void __launch_bounds__(NWAVES * 64, 2) fwd_kernel(Args args) {
;     ...
;                     __syncthreads();
;                 }
;     ...
;                 if (layer == 0) {
;                 }
;             }
;             PHASE_END
.LBB0_1289:
	v_readlane_b32 s0, v254, 2
	s_add_i32 s4, s0, 1
	s_cmp_lt_i32 s4, s81
	s_cbranch_scc0 .LBB0_1372
	v_readlane_b32 s100, v255, 8
	s_cmp_eq_u32 s100, 0
	s_cbranch_scc0 .Lp0_orig
	v_readlane_b32 s100, v255, 57
	s_cmp_lg_u32 s100, 0
	s_cbranch_scc0 .Lp0_orig
	s_waitcnt vmcnt(0) lgkmcnt(0)
	s_barrier
	v_readlane_b32 s100, v255, 59
	s_add_i32 s100, s100, 1
	v_writelane_b32 v255, s100, 59
	v_cmp_eq_u32_e32 vcc, 0, v215
	s_and_saveexec_b64 s[0:1], vcc
	s_cbranch_execz .Lp0_w
	s_load_dwordx2 s[2:3], s[94:95], 0xb8
	s_lshl_b32 s100, s100, 2
	v_readlane_b32 s101, v255, 12
	s_and_b32 s6, s101, 63
	s_lshl_b32 s6, s6, 6
	s_cmp_lt_u32 s6, 0x800
	s_movk_i32 s7, 0x1400
	s_cselect_b32 s7, 0xc00, s7
	s_add_i32 s6, s6, s7
	v_mov_b32_e32 v0, s6
	v_mov_b32_e32 v1, 1
	s_and_b32 s6, s101, 7
	s_lshl_b32 s6, s6, 3
	s_bfe_u32 s7, s101, 0x30003
	s_add_i32 s8, s6, s7
	s_sub_i32 s6, s8, 1
	s_max_i32 s6, s6, 0
	s_lshr_b32 s7, s6, 3
	s_and_b32 s6, s6, 7
	s_lshl_b32 s6, s6, 3
	s_add_i32 s6, s6, s7
	s_lshl_b32 s6, s6, 6
	s_cmp_lt_u32 s6, 0x800
	s_movk_i32 s7, 0x1400
	s_cselect_b32 s7, 0xc00, s7
	s_add_i32 s6, s6, s7
	v_mov_b32_e32 v3, s6
	s_add_i32 s6, s8, 1
	s_min_i32 s6, s6, 63
	s_lshr_b32 s7, s6, 3
	s_and_b32 s6, s6, 7
	s_lshl_b32 s6, s6, 3
	s_add_i32 s6, s6, s7
	s_lshl_b32 s6, s6, 6
	s_cmp_lt_u32 s6, 0x800
	s_movk_i32 s7, 0x1400
	s_cselect_b32 s7, 0xc00, s7
	s_add_i32 s6, s6, s7
	v_mov_b32_e32 v4, s6
	s_bfe_u32 s6, s101, 0x10002
	s_lshl_b32 s6, s6, 5
	s_addk_i32 s6, 0x2c18
	v_mov_b32_e32 v5, s6
	s_lshr_b32 s6, s101, 2
	s_lshl_b32 s6, s6, 5
	s_addk_i32 s6, 0x2c18
	v_mov_b32_e32 v6, s6
	s_waitcnt lgkmcnt(0)
	s_add_u32 s2, s2, 0xe0000
	s_addc_u32 s3, s3, 0
	global_atomic_add v0, v1, s[2:3]
	s_sub_i32 s6, s101, 32
	s_cmp_lt_u32 s6, 32
	s_cbranch_scc0 .Lp0_nc
	global_atomic_add v5, v1, s[2:3]
